# grid-barrier seams: L1 invalidate at arrival, non-leaders poll the cross-XCD release word directly
# baseline (speedup 1.0000x reference)
.LBB0_129:
	s_or_b64 exec, exec, s[8:9]
	buffer_inv sc1
	v_cvt_f32_u32_e32 v4, v2
	s_waitcnt vmcnt(1)
	v_readfirstlane_b32 s6, v3
	v_sub_u32_e32 v3, 0, v2
	v_rcp_iflag_f32_e32 v4, v4
	v_add_u32_e32 v5, s6, v1
	v_mul_f32_e32 v4, 0x4f7ffffe, v4
	v_cvt_u32_f32_e32 v4, v4
	v_mul_lo_u32 v1, v3, v4
	v_mul_hi_u32 v1, v4, v1
	v_add_u32_e32 v1, v4, v1
	v_mul_hi_u32 v1, v5, v1
	v_mul_lo_u32 v3, v1, v2
	v_sub_u32_e32 v3, v5, v3
	v_add_u32_e32 v4, 1, v1
	v_cmp_ge_u32_e32 vcc, v3, v2
	s_nop 1
	v_cndmask_b32_e32 v1, v1, v4, vcc
	v_sub_u32_e32 v4, v3, v2
	v_cndmask_b32_e32 v3, v3, v4, vcc
	v_add_u32_e32 v4, 1, v1
	v_cmp_ge_u32_e32 vcc, v3, v2
	v_add_u32_e32 v3, 1, v5
	s_nop 0
	v_cndmask_b32_e32 v1, v1, v4, vcc
	v_mul_lo_u32 v4, v2, v1
	v_add_u32_e32 v2, v4, v2
	v_cmp_ne_u32_e32 vcc, v3, v2
	s_and_saveexec_b64 s[6:7], vcc
	s_xor_b64 s[6:7], exec, s[6:7]
	s_cbranch_execz .LBB0_143
	s_waitcnt lgkmcnt(0)
	v_mov_b32_e32 v0, 0x2000
	global_load_dword v0, v0, s[4:5] offset:1024 sc1
	s_add_u32 s12, s2, 0x7500
	s_addc_u32 s13, s3, 0
	s_waitcnt vmcnt(0)
	v_cmp_eq_u32_e32 vcc, v0, v1
	s_and_saveexec_b64 s[8:9], vcc
	s_cbranch_execz .LBB0_142
	s_add_u32 s10, s2, 0x4200
	s_addc_u32 s11, s3, 0
	s_mov_b32 s24, 1
	s_mov_b64 s[14:15], 0
	v_mov_b32_e32 v0, 0
	s_branch .LBB0_133

.LBB0_160:
	s_or_b64 exec, exec, s[2:3]
	s_mov_b64 s[2:3], exec
	v_mbcnt_lo_u32_b32 v0, s2, 0
	v_mbcnt_hi_u32_b32 v0, s3, v0
	v_cmp_eq_u32_e32 vcc, 0, v0
	s_waitcnt vmcnt(0)
	s_and_saveexec_b64 s[6:7], vcc
	s_cbranch_execz .LBB0_162
	s_bcnt1_i32_b64 s2, s[2:3]
	v_mov_b32_e32 v0, 0x2000
	v_mov_b32_e32 v1, s2
	global_atomic_add v0, v1, s[4:5] offset:1024

.LBB0_268:
	s_or_b64 exec, exec, s[10:11]
	buffer_inv sc1
	v_cvt_f32_u32_e32 v5, v3
	s_waitcnt vmcnt(1)
	v_readfirstlane_b32 s8, v4
	v_sub_u32_e32 v4, 0, v3
	v_rcp_iflag_f32_e32 v5, v5
	v_add_u32_e32 v6, s8, v2
	v_mul_f32_e32 v5, 0x4f7ffffe, v5
	v_cvt_u32_f32_e32 v5, v5
	v_mul_lo_u32 v2, v4, v5
	v_mul_hi_u32 v2, v5, v2
	v_add_u32_e32 v2, v5, v2
	v_mul_hi_u32 v2, v6, v2
	v_mul_lo_u32 v4, v2, v3
	v_sub_u32_e32 v4, v6, v4
	v_add_u32_e32 v5, 1, v2
	v_cmp_ge_u32_e32 vcc, v4, v3
	s_nop 1
	v_cndmask_b32_e32 v2, v2, v5, vcc
	v_sub_u32_e32 v5, v4, v3
	v_cndmask_b32_e32 v4, v4, v5, vcc
	v_add_u32_e32 v5, 1, v2
	v_cmp_ge_u32_e32 vcc, v4, v3
	v_add_u32_e32 v4, 1, v6
	s_nop 0
	v_cndmask_b32_e32 v2, v2, v5, vcc
	v_mul_lo_u32 v5, v3, v2
	v_add_u32_e32 v3, v5, v3
	v_cmp_ne_u32_e32 vcc, v4, v3
	s_and_saveexec_b64 s[8:9], vcc
	s_xor_b64 s[8:9], exec, s[8:9]
	s_cbranch_execz .LBB0_282
	s_waitcnt lgkmcnt(0)
	global_load_dword v0, v252, s[4:5] offset:1024 sc1
	s_add_u32 s14, s2, 0x7500
	s_addc_u32 s15, s3, 0
	s_waitcnt vmcnt(0)
	v_cmp_eq_u32_e32 vcc, v0, v2
	s_and_saveexec_b64 s[10:11], vcc
	s_cbranch_execz .LBB0_281
	s_add_u32 s12, s2, 0x4200
	s_addc_u32 s13, s3, 0
	s_mov_b32 s26, 1
	s_mov_b64 s[16:17], 0
	s_branch .LBB0_272

.LBB0_299:
	s_or_b64 exec, exec, s[2:3]
	s_mov_b64 s[2:3], exec
	v_mbcnt_lo_u32_b32 v0, s2, 0
	v_mbcnt_hi_u32_b32 v0, s3, v0
	v_cmp_eq_u32_e32 vcc, 0, v0
	s_waitcnt vmcnt(0)
	s_and_saveexec_b64 s[8:9], vcc
	s_cbranch_execz .LBB0_301
	s_bcnt1_i32_b64 s2, s[2:3]
	v_mov_b32_e32 v0, s2
	global_atomic_add v252, v0, s[4:5] offset:1024

.LBB0_545:
	s_or_b64 exec, exec, s[8:9]
	buffer_inv sc1
	v_cvt_f32_u32_e32 v5, v3
	s_waitcnt vmcnt(1)
	v_readfirstlane_b32 s6, v4
	v_sub_u32_e32 v4, 0, v3
	v_rcp_iflag_f32_e32 v5, v5
	v_add_u32_e32 v6, s6, v2
	v_mul_f32_e32 v5, 0x4f7ffffe, v5
	v_cvt_u32_f32_e32 v5, v5
	v_mul_lo_u32 v2, v4, v5
	v_mul_hi_u32 v2, v5, v2
	v_add_u32_e32 v2, v5, v2
	v_mul_hi_u32 v2, v6, v2
	v_mul_lo_u32 v4, v2, v3
	v_sub_u32_e32 v4, v6, v4
	v_add_u32_e32 v5, 1, v2
	v_cmp_ge_u32_e32 vcc, v4, v3
	s_nop 1
	v_cndmask_b32_e32 v2, v2, v5, vcc
	v_sub_u32_e32 v5, v4, v3
	v_cndmask_b32_e32 v4, v4, v5, vcc
	v_add_u32_e32 v5, 1, v2
	v_cmp_ge_u32_e32 vcc, v4, v3
	v_add_u32_e32 v4, 1, v6
	s_nop 0
	v_cndmask_b32_e32 v2, v2, v5, vcc
	v_mul_lo_u32 v5, v3, v2
	v_add_u32_e32 v3, v5, v3
	v_cmp_ne_u32_e32 vcc, v4, v3
	s_and_saveexec_b64 s[6:7], vcc
	s_xor_b64 s[6:7], exec, s[6:7]
	s_cbranch_execz .LBB0_559
	s_waitcnt lgkmcnt(0)
	global_load_dword v0, v252, s[4:5] offset:1024 sc1
	s_add_u32 s12, s2, 0x7500
	s_addc_u32 s13, s3, 0
	s_waitcnt vmcnt(0)
	v_cmp_eq_u32_e32 vcc, v0, v2
	s_and_saveexec_b64 s[8:9], vcc
	s_cbranch_execz .LBB0_558
	s_add_u32 s10, s2, 0x4200
	s_addc_u32 s11, s3, 0
	s_mov_b32 s24, 1
	s_mov_b64 s[14:15], 0
	s_branch .LBB0_549

.LBB0_576:
	s_or_b64 exec, exec, s[2:3]
	s_mov_b64 s[2:3], exec
	v_mbcnt_lo_u32_b32 v0, s2, 0
	v_mbcnt_hi_u32_b32 v0, s3, v0
	v_cmp_eq_u32_e32 vcc, 0, v0
	s_waitcnt vmcnt(0)
	s_and_saveexec_b64 s[6:7], vcc
	s_cbranch_execz .LBB0_578
	s_bcnt1_i32_b64 s2, s[2:3]
	v_mov_b32_e32 v0, s2
	global_atomic_add v252, v0, s[4:5] offset:1024

.LBB0_974:
	s_or_b64 exec, exec, s[2:3]
	s_mov_b64 s[2:3], exec
	v_mbcnt_lo_u32_b32 v0, s2, 0
	v_mbcnt_hi_u32_b32 v0, s3, v0
	v_cmp_eq_u32_e32 vcc, 0, v0
	s_waitcnt vmcnt(0)
	s_and_saveexec_b64 s[6:7], vcc
	s_cbranch_execz .LBB0_165
	s_bcnt1_i32_b64 s2, s[2:3]
	v_mov_b32_e32 v0, s2
	global_atomic_add v252, v0, s[4:5] offset:1024
	s_branch .LBB0_165
